# norm phases: modulation-table build loop (4 serial load->wait trips) written out straight-line, all 9 loads issued back to back with counted waits
# speedup vs baseline: 1.0141x; 1.0052x over previous
; #define LAS __attribute__((address_space(3)))
; __device__ __forceinline__ void phase_norm(const Params& P, LAS unsigned char* lds, int l, int i, const void* xsrc, int src16, int out8) {
;     ...
;     for (int q = tid; q < NBATCH * DM / 4; q += NTHREADS) { const int b = q / (DM / 4), c = 4 * (q % (DM / 4));
;         const f32x4 gg = *(const f32x4*)(g + c), s1 = *(const f32x4*)(mod + (size_t)b * NMOD + (size_t)(3 * i + 1) * DM + c), s0 = *(const f32x4*)(mod + (size_t)b * NMOD + (size_t)(3 * i + 0) * DM + c);
;         *(LAS f32x4*)(gs + b * DM + c) = gg * (s1 + 1.0f); *(LAS f32x4*)(shl + b * DM + c) = s0; }
.LBB0_331:
	s_andn2_b64 vcc, exec, s[0:1]
	s_cbranch_vccnz .LBB0_422
	s_waitcnt lgkmcnt(0)
	v_mov_b32_e32 v2, v0
	s_movk_i32 s0, 0x800
	s_nop 0
	v_cmp_gt_i32_e32 vcc, s0, v2
	s_and_saveexec_b64 s[0:1], vcc
	s_cbranch_execz .LBB0_335
	v_readlane_b32 s60, v250, 39
	s_mul_i32 s2, s94, 0x6000
	v_readlane_b32 s68, v250, 47
	v_readlane_b32 s69, v250, 48
	s_add_u32 s8, s68, s2
	s_addc_u32 s9, s69, 0
	s_mul_i32 s2, s94, 0x48000
	v_readlane_b32 s4, v251, 30
	v_readlane_b32 s5, v251, 31
	s_add_u32 s12, s4, s2
	s_addc_u32 s13, s5, 0
	v_lshl_add_u32 v4, v2, 4, 0
	v_lshlrev_b32_e32 v5, 2, v2
	s_mov_b64 s[20:21], 0
	v_mov_b32_e32 v6, v2
	v_readlane_b32 s61, v250, 40
	v_readlane_b32 s62, v250, 41
	v_readlane_b32 s63, v250, 42
	v_readlane_b32 s64, v250, 43
	v_readlane_b32 s65, v250, 44
	v_readlane_b32 s66, v250, 45
	v_readlane_b32 s67, v250, 46
	v_readlane_b32 s70, v250, 49
	v_readlane_b32 s71, v250, 50
	v_readlane_b32 s72, v250, 51
	v_readlane_b32 s73, v250, 52
	v_readlane_b32 s74, v250, 53
	v_readlane_b32 s75, v250, 54
	s_waitcnt vmcnt(0) lgkmcnt(0)
	v_lshlrev_b32_e32 v8, 4, v2
	v_mov_b32_e32 v9, 0
	v_lshl_add_u64 v[10:11], s[8:9], 0, v[8:9]
	v_lshl_add_u64 v[14:15], s[12:13], 0, v[8:9]
	global_load_dwordx4 v[16:19], v[10:11], off
	v_add_co_u32_e32 v10, vcc, s87, v14
	s_nop 1
	v_addc_co_u32_e32 v11, vcc, 0, v15, vcc
	global_load_dwordx4 v[20:23], v[10:11], off
	global_load_dwordx4 v[28:31], v[14:15], off
	v_add_co_u32_e32 v14, vcc, 0x12000, v14
	s_nop 1
	v_addc_co_u32_e32 v15, vcc, 0, v15, vcc
	v_add_co_u32_e32 v10, vcc, s87, v14
	s_nop 1
	v_addc_co_u32_e32 v11, vcc, 0, v15, vcc
	global_load_dwordx4 v[32:35], v[10:11], off
	global_load_dwordx4 v[36:39], v[14:15], off
	v_add_co_u32_e32 v14, vcc, 0x12000, v14
	s_nop 1
	v_addc_co_u32_e32 v15, vcc, 0, v15, vcc
	v_add_co_u32_e32 v10, vcc, s87, v14
	s_nop 1
	v_addc_co_u32_e32 v11, vcc, 0, v15, vcc
	global_load_dwordx4 v[40:43], v[10:11], off
	global_load_dwordx4 v[60:63], v[14:15], off
	v_add_co_u32_e32 v14, vcc, 0x12000, v14
	s_nop 1
	v_addc_co_u32_e32 v15, vcc, 0, v15, vcc
	v_add_co_u32_e32 v10, vcc, s87, v14
	s_nop 1
	v_addc_co_u32_e32 v11, vcc, 0, v15, vcc
	global_load_dwordx4 v[64:67], v[10:11], off
	global_load_dwordx4 v[72:75], v[14:15], off
	s_waitcnt vmcnt(6)
	v_pk_add_f32 v[22:23], v[22:23], 1.0 op_sel_hi:[1,0]
	v_pk_add_f32 v[20:21], v[20:21], 1.0 op_sel_hi:[1,0]
	v_pk_mul_f32 v[22:23], v[18:19], v[22:23]
	v_pk_mul_f32 v[20:21], v[16:17], v[20:21]
	ds_write_b128 v4, v[28:31] offset:32768
	ds_write_b128 v4, v[20:23]
	s_waitcnt vmcnt(4)
	v_pk_add_f32 v[34:35], v[34:35], 1.0 op_sel_hi:[1,0]
	v_pk_add_f32 v[32:33], v[32:33], 1.0 op_sel_hi:[1,0]
	v_pk_mul_f32 v[34:35], v[18:19], v[34:35]
	v_pk_mul_f32 v[32:33], v[16:17], v[32:33]
	ds_write_b128 v4, v[36:39] offset:40960
	ds_write_b128 v4, v[32:35] offset:8192
	s_waitcnt vmcnt(2)
	v_pk_add_f32 v[42:43], v[42:43], 1.0 op_sel_hi:[1,0]
	v_pk_add_f32 v[40:41], v[40:41], 1.0 op_sel_hi:[1,0]
	v_pk_mul_f32 v[42:43], v[18:19], v[42:43]
	v_pk_mul_f32 v[40:41], v[16:17], v[40:41]
	ds_write_b128 v4, v[60:63] offset:49152
	ds_write_b128 v4, v[40:43] offset:16384
	s_waitcnt vmcnt(0)
	v_pk_add_f32 v[66:67], v[66:67], 1.0 op_sel_hi:[1,0]
	v_pk_add_f32 v[64:65], v[64:65], 1.0 op_sel_hi:[1,0]
	v_pk_mul_f32 v[66:67], v[18:19], v[66:67]
	v_pk_mul_f32 v[64:65], v[16:17], v[64:65]
	ds_write_b128 v4, v[72:75] offset:57344
	ds_write_b128 v4, v[64:67] offset:24576

; #define LAS __attribute__((address_space(3)))
; __device__ __forceinline__ void phase_norm(const Params& P, LAS unsigned char* lds, int l, int i, const void* xsrc, int src16, int out8) {
;     ...
;     for (int q = tid; q < NBATCH * DM / 4; q += NTHREADS) { const int b = q / (DM / 4), c = 4 * (q % (DM / 4));
;         const f32x4 gg = *(const f32x4*)(g + c), s1 = *(const f32x4*)(mod + (size_t)b * NMOD + (size_t)(3 * i + 1) * DM + c), s0 = *(const f32x4*)(mod + (size_t)b * NMOD + (size_t)(3 * i + 0) * DM + c);
;         *(LAS f32x4*)(gs + b * DM + c) = gg * (s1 + 1.0f); *(LAS f32x4*)(shl + b * DM + c) = s0; }
.LBB0_592:
	s_andn2_b64 vcc, exec, s[0:1]
	s_cbranch_vccnz .LBB0_693
	v_mov_b32_e32 v6, v0
	s_movk_i32 s0, 0x800
	s_nop 0
	v_cmp_gt_i32_e32 vcc, s0, v6
	s_and_saveexec_b64 s[0:1], vcc
	s_cbranch_execz .LBB0_596
	v_readlane_b32 s2, v247, 31
	v_readlane_b32 s60, v250, 39
	s_mov_b32 s4, s2
	s_mulk_i32 s2, 0x6000
	v_readlane_b32 s68, v250, 47
	v_readlane_b32 s3, v247, 32
	v_readlane_b32 s69, v250, 48
	s_add_u32 s2, s68, s2
	s_addc_u32 s3, s69, 0
	s_add_u32 s8, s2, 0x2000
	s_addc_u32 s9, s3, 0
	s_mul_i32 s2, s4, 0x48000
	v_readlane_b32 s4, v251, 30
	v_readlane_b32 s5, v251, 31
	s_add_u32 s2, s4, s2
	s_addc_u32 s3, s5, 0
	s_add_u32 s12, s2, 0x6000
	s_addc_u32 s13, s3, 0
	v_lshl_add_u32 v2, v6, 4, 0
	v_lshlrev_b32_e32 v4, 2, v6
	s_mov_b64 s[20:21], 0
	v_mov_b32_e32 v5, v6
	v_readlane_b32 s61, v250, 40
	v_readlane_b32 s62, v250, 41
	v_readlane_b32 s63, v250, 42
	v_readlane_b32 s64, v250, 43
	v_readlane_b32 s65, v250, 44
	v_readlane_b32 s66, v250, 45
	v_readlane_b32 s67, v250, 46
	v_readlane_b32 s70, v250, 49
	v_readlane_b32 s71, v250, 50
	v_readlane_b32 s72, v250, 51
	v_readlane_b32 s73, v250, 52
	v_readlane_b32 s74, v250, 53
	v_readlane_b32 s75, v250, 54
	s_waitcnt vmcnt(0) lgkmcnt(0)
	v_lshlrev_b32_e32 v8, 4, v6
	v_mov_b32_e32 v9, 0
	v_lshl_add_u64 v[10:11], s[8:9], 0, v[8:9]
	v_lshl_add_u64 v[14:15], s[12:13], 0, v[8:9]
	global_load_dwordx4 v[16:19], v[10:11], off
	v_add_co_u32_e32 v10, vcc, s87, v14
	s_nop 1
	v_addc_co_u32_e32 v11, vcc, 0, v15, vcc
	global_load_dwordx4 v[20:23], v[10:11], off
	global_load_dwordx4 v[28:31], v[14:15], off
	v_add_co_u32_e32 v14, vcc, 0x12000, v14
	s_nop 1
	v_addc_co_u32_e32 v15, vcc, 0, v15, vcc
	v_add_co_u32_e32 v10, vcc, s87, v14
	s_nop 1
	v_addc_co_u32_e32 v11, vcc, 0, v15, vcc
	global_load_dwordx4 v[32:35], v[10:11], off
	global_load_dwordx4 v[36:39], v[14:15], off
	v_add_co_u32_e32 v14, vcc, 0x12000, v14
	s_nop 1
	v_addc_co_u32_e32 v15, vcc, 0, v15, vcc
	v_add_co_u32_e32 v10, vcc, s87, v14
	s_nop 1
	v_addc_co_u32_e32 v11, vcc, 0, v15, vcc
	global_load_dwordx4 v[40:43], v[10:11], off
	global_load_dwordx4 v[60:63], v[14:15], off
	v_add_co_u32_e32 v14, vcc, 0x12000, v14
	s_nop 1
	v_addc_co_u32_e32 v15, vcc, 0, v15, vcc
	v_add_co_u32_e32 v10, vcc, s87, v14
	s_nop 1
	v_addc_co_u32_e32 v11, vcc, 0, v15, vcc
	global_load_dwordx4 v[64:67], v[10:11], off
	global_load_dwordx4 v[72:75], v[14:15], off
	s_waitcnt vmcnt(6)
	v_pk_add_f32 v[22:23], v[22:23], 1.0 op_sel_hi:[1,0]
	v_pk_add_f32 v[20:21], v[20:21], 1.0 op_sel_hi:[1,0]
	v_pk_mul_f32 v[22:23], v[18:19], v[22:23]
	v_pk_mul_f32 v[20:21], v[16:17], v[20:21]
	ds_write_b128 v2, v[28:31] offset:32768
	ds_write_b128 v2, v[20:23]
	s_waitcnt vmcnt(4)
	v_pk_add_f32 v[34:35], v[34:35], 1.0 op_sel_hi:[1,0]
	v_pk_add_f32 v[32:33], v[32:33], 1.0 op_sel_hi:[1,0]
	v_pk_mul_f32 v[34:35], v[18:19], v[34:35]
	v_pk_mul_f32 v[32:33], v[16:17], v[32:33]
	ds_write_b128 v2, v[36:39] offset:40960
	ds_write_b128 v2, v[32:35] offset:8192
	s_waitcnt vmcnt(2)
	v_pk_add_f32 v[42:43], v[42:43], 1.0 op_sel_hi:[1,0]
	v_pk_add_f32 v[40:41], v[40:41], 1.0 op_sel_hi:[1,0]
	v_pk_mul_f32 v[42:43], v[18:19], v[42:43]
	v_pk_mul_f32 v[40:41], v[16:17], v[40:41]
	ds_write_b128 v2, v[60:63] offset:49152
	ds_write_b128 v2, v[40:43] offset:16384
	s_waitcnt vmcnt(0)
	v_pk_add_f32 v[66:67], v[66:67], 1.0 op_sel_hi:[1,0]
	v_pk_add_f32 v[64:65], v[64:65], 1.0 op_sel_hi:[1,0]
	v_pk_mul_f32 v[66:67], v[18:19], v[66:67]
	v_pk_mul_f32 v[64:65], v[16:17], v[64:65]
	ds_write_b128 v2, v[72:75] offset:57344
	ds_write_b128 v2, v[64:67] offset:24576

; #define LAS __attribute__((address_space(3)))
; __device__ __forceinline__ void phase_norm(const Params& P, LAS unsigned char* lds, int l, int i, const void* xsrc, int src16, int out8) {
;     ...
;     for (int q = tid; q < NBATCH * DM / 4; q += NTHREADS) { const int b = q / (DM / 4), c = 4 * (q % (DM / 4));
;         const f32x4 gg = *(const f32x4*)(g + c), s1 = *(const f32x4*)(mod + (size_t)b * NMOD + (size_t)(3 * i + 1) * DM + c), s0 = *(const f32x4*)(mod + (size_t)b * NMOD + (size_t)(3 * i + 0) * DM + c);
;         *(LAS f32x4*)(gs + b * DM + c) = gg * (s1 + 1.0f); *(LAS f32x4*)(shl + b * DM + c) = s0; }
.LBB0_1189:
	s_andn2_b64 vcc, exec, s[0:1]
	s_cbranch_vccnz .LBB0_1254
	s_waitcnt lgkmcnt(0)
	v_mov_b32_e32 v2, v0
	s_movk_i32 s0, 0x800
	s_nop 0
	v_cmp_gt_i32_e32 vcc, s0, v2
	s_and_saveexec_b64 s[0:1], vcc
	s_cbranch_execz .LBB0_1193
	v_readlane_b32 s2, v247, 31
	v_readlane_b32 s60, v250, 39
	s_mov_b32 s4, s2
	s_mulk_i32 s2, 0x6000
	v_readlane_b32 s68, v250, 47
	v_readlane_b32 s3, v247, 32
	v_readlane_b32 s69, v250, 48
	s_add_u32 s2, s68, s2
	s_addc_u32 s3, s69, 0
	s_add_u32 s8, s2, 0x4000
	s_addc_u32 s9, s3, 0
	s_mul_i32 s2, s4, 0x48000
	v_readlane_b32 s4, v251, 30
	v_readlane_b32 s5, v251, 31
	s_add_u32 s2, s4, s2
	s_addc_u32 s3, s5, 0
	s_add_u32 s12, s2, 0xc000
	s_addc_u32 s13, s3, 0
	v_lshl_add_u32 v4, v2, 4, 0
	v_lshlrev_b32_e32 v5, 2, v2
	s_mov_b64 s[20:21], 0
	v_mov_b32_e32 v6, v2
	v_readlane_b32 s61, v250, 40
	v_readlane_b32 s62, v250, 41
	v_readlane_b32 s63, v250, 42
	v_readlane_b32 s64, v250, 43
	v_readlane_b32 s65, v250, 44
	v_readlane_b32 s66, v250, 45
	v_readlane_b32 s67, v250, 46
	v_readlane_b32 s70, v250, 49
	v_readlane_b32 s71, v250, 50
	v_readlane_b32 s72, v250, 51
	v_readlane_b32 s73, v250, 52
	v_readlane_b32 s74, v250, 53
	v_readlane_b32 s75, v250, 54
	s_waitcnt vmcnt(0) lgkmcnt(0)
	v_lshlrev_b32_e32 v8, 4, v2
	v_mov_b32_e32 v9, 0
	v_lshl_add_u64 v[10:11], s[8:9], 0, v[8:9]
	v_lshl_add_u64 v[14:15], s[12:13], 0, v[8:9]
	global_load_dwordx4 v[16:19], v[10:11], off
	v_add_co_u32_e32 v10, vcc, s87, v14
	s_nop 1
	v_addc_co_u32_e32 v11, vcc, 0, v15, vcc
	global_load_dwordx4 v[20:23], v[10:11], off
	global_load_dwordx4 v[28:31], v[14:15], off
	v_add_co_u32_e32 v14, vcc, 0x12000, v14
	s_nop 1
	v_addc_co_u32_e32 v15, vcc, 0, v15, vcc
	v_add_co_u32_e32 v10, vcc, s87, v14
	s_nop 1
	v_addc_co_u32_e32 v11, vcc, 0, v15, vcc
	global_load_dwordx4 v[32:35], v[10:11], off
	global_load_dwordx4 v[36:39], v[14:15], off
	v_add_co_u32_e32 v14, vcc, 0x12000, v14
	s_nop 1
	v_addc_co_u32_e32 v15, vcc, 0, v15, vcc
	v_add_co_u32_e32 v10, vcc, s87, v14
	s_nop 1
	v_addc_co_u32_e32 v11, vcc, 0, v15, vcc
	global_load_dwordx4 v[40:43], v[10:11], off
	global_load_dwordx4 v[60:63], v[14:15], off
	v_add_co_u32_e32 v14, vcc, 0x12000, v14
	s_nop 1
	v_addc_co_u32_e32 v15, vcc, 0, v15, vcc
	v_add_co_u32_e32 v10, vcc, s87, v14
	s_nop 1
	v_addc_co_u32_e32 v11, vcc, 0, v15, vcc
	global_load_dwordx4 v[64:67], v[10:11], off
	global_load_dwordx4 v[72:75], v[14:15], off
	s_waitcnt vmcnt(6)
	v_pk_add_f32 v[22:23], v[22:23], 1.0 op_sel_hi:[1,0]
	v_pk_add_f32 v[20:21], v[20:21], 1.0 op_sel_hi:[1,0]
	v_pk_mul_f32 v[22:23], v[18:19], v[22:23]
	v_pk_mul_f32 v[20:21], v[16:17], v[20:21]
	ds_write_b128 v4, v[28:31] offset:32768
	ds_write_b128 v4, v[20:23]
	s_waitcnt vmcnt(4)
	v_pk_add_f32 v[34:35], v[34:35], 1.0 op_sel_hi:[1,0]
	v_pk_add_f32 v[32:33], v[32:33], 1.0 op_sel_hi:[1,0]
	v_pk_mul_f32 v[34:35], v[18:19], v[34:35]
	v_pk_mul_f32 v[32:33], v[16:17], v[32:33]
	ds_write_b128 v4, v[36:39] offset:40960
	ds_write_b128 v4, v[32:35] offset:8192
	s_waitcnt vmcnt(2)
	v_pk_add_f32 v[42:43], v[42:43], 1.0 op_sel_hi:[1,0]
	v_pk_add_f32 v[40:41], v[40:41], 1.0 op_sel_hi:[1,0]
	v_pk_mul_f32 v[42:43], v[18:19], v[42:43]
	v_pk_mul_f32 v[40:41], v[16:17], v[40:41]
	ds_write_b128 v4, v[60:63] offset:49152
	ds_write_b128 v4, v[40:43] offset:16384
	s_waitcnt vmcnt(0)
	v_pk_add_f32 v[66:67], v[66:67], 1.0 op_sel_hi:[1,0]
	v_pk_add_f32 v[64:65], v[64:65], 1.0 op_sel_hi:[1,0]
	v_pk_mul_f32 v[66:67], v[18:19], v[66:67]
	v_pk_mul_f32 v[64:65], v[16:17], v[64:65]
	ds_write_b128 v4, v[72:75] offset:57344
	ds_write_b128 v4, v[64:67] offset:24576
